# v105 + corrected MFMA-first: QK MFMAs of the first loop step move up together with their counted lgkmcnt waits
# speedup vs baseline: 1.0369x; 1.0040x over previous
.LBB0_647:
	s_mov_b32 s25, s24
	s_mov_b32 s1, s2
	v_lshl_add_u32 v214, s27, 1, v248
	ds_read_b64_tr_b16 v[66:67], v214 offset:24576
	ds_read_b64_tr_b16 v[68:69], v214 offset:25088
	s_waitcnt lgkmcnt(9)
	v_mfma_f32_32x32x16_bf16 v[128:143], v[204:207], v[172:175], 0
	v_add_f32_e32 v65, v96, v97
	v_add_f32_e32 v65, v98, v65
	v_add_f32_e32 v65, v99, v65
	v_add_f32_e32 v65, v100, v65
	v_add_f32_e32 v65, v101, v65
	v_cvt_pk_bf16_f32 v160, v96, v97
	v_cvt_pk_bf16_f32 v161, v98, v99
	ds_read_b64_tr_b16 v[70:71], v214 offset:28672
	ds_read_b64_tr_b16 v[72:73], v214 offset:29184
	s_waitcnt lgkmcnt(10)
	v_mfma_f32_32x32x16_bf16 v[112:127], v[200:203], v[172:175], 0
	v_add_f32_e32 v65, v102, v65
	v_add_f32_e32 v65, v103, v65
	v_add_f32_e32 v65, v104, v65
	v_add_f32_e32 v65, v105, v65
	v_cvt_pk_bf16_f32 v162, v100, v101
	v_cvt_pk_bf16_f32 v163, v102, v103
	ds_read_b64_tr_b16 v[74:75], v214 offset:25600
	ds_read_b64_tr_b16 v[76:77], v214 offset:26112
	s_waitcnt lgkmcnt(11)
	v_mfma_f32_32x32x16_bf16 v[128:143], v[196:199], v[168:171], v[128:143]
	v_add_f32_e32 v65, v106, v65
	v_add_f32_e32 v65, v107, v65
	v_add_f32_e32 v65, v108, v65
	v_add_f32_e32 v65, v109, v65
	v_cvt_pk_bf16_f32 v152, v104, v105
	v_cvt_pk_bf16_f32 v153, v106, v107
	ds_read_b64_tr_b16 v[96:97], v214 offset:29696
	ds_read_b64_tr_b16 v[98:99], v214 offset:30208
	s_waitcnt lgkmcnt(12)
	v_mfma_f32_32x32x16_bf16 v[112:127], v[192:195], v[168:171], v[112:127]
	v_add_f32_e32 v65, v110, v65
	v_add_f32_e32 v65, v111, v65
	v_add_f32_e32 v65, v80, v65
	v_add_f32_e32 v65, v81, v65
	v_cvt_pk_bf16_f32 v154, v108, v109
	v_cvt_pk_bf16_f32 v155, v110, v111
	ds_read_b64_tr_b16 v[100:101], v214 offset:26624
	ds_read_b64_tr_b16 v[102:103], v214 offset:27136
	s_waitcnt lgkmcnt(13)
	v_mfma_f32_32x32x16_bf16 v[128:143], v[188:191], v[164:167], v[128:143]
	v_add_f32_e32 v65, v82, v65
	v_add_f32_e32 v65, v83, v65
	v_add_f32_e32 v65, v84, v65
	v_add_f32_e32 v65, v85, v65
	v_cvt_pk_bf16_f32 v148, v80, v81
	v_cvt_pk_bf16_f32 v149, v82, v83
	ds_read_b64_tr_b16 v[104:105], v214 offset:30720
	ds_read_b64_tr_b16 v[106:107], v214 offset:31232
	s_waitcnt lgkmcnt(14)
	v_mfma_f32_32x32x16_bf16 v[112:127], v[184:187], v[164:167], v[112:127]
	v_add_f32_e32 v65, v86, v65
	v_add_f32_e32 v65, v87, v65
	v_add_f32_e32 v65, v88, v65
	v_add_f32_e32 v65, v89, v65
	v_cvt_pk_bf16_f32 v150, v84, v85
	v_cvt_pk_bf16_f32 v151, v86, v87
	ds_read_b64_tr_b16 v[108:109], v214 offset:27648
	ds_read_b64_tr_b16 v[110:111], v214 offset:28160
	s_waitcnt lgkmcnt(14)
	v_mfma_f32_32x32x16_bf16 v[128:143], v[180:183], v[156:159], v[128:143]
	v_add_f32_e32 v65, v90, v65
	v_add_f32_e32 v65, v91, v65
	v_add_f32_e32 v65, v92, v65
	v_add_f32_e32 v65, v93, v65
	v_cvt_pk_bf16_f32 v144, v88, v89
	v_cvt_pk_bf16_f32 v145, v90, v91
	ds_read_b64_tr_b16 v[86:87], v214 offset:31744
	ds_read_b64_tr_b16 v[88:89], v214 offset:32256
	v_mfma_f32_32x32x16_bf16 v[112:127], v[176:179], v[156:159], v[112:127]
	v_add_f32_e32 v65, v94, v65
	v_add_f32_e32 v65, v95, v65
	v_add_f32_e32 v65, 0, v65
	v_cvt_pk_bf16_f32 v146, v92, v93
	v_cvt_pk_bf16_f32 v147, v94, v95
	s_add_i32 s2, s2, s69
	v_lshl_add_u64 v[78:79], v[212:213], 0, s[16:17]
	s_mov_b32 s24, m0
	s_mov_b32 m0, s2
	s_nop 0
	global_load_lds_dwordx4 v[78:79], off
	s_mov_b32 m0, s24
	s_lshl_b32 s2, s25, 1
	v_lshl_add_u64 v[78:79], v[210:211], 0, s[16:17]
	s_add_i32 s24, s2, s72
	s_mov_b32 s27, m0
	s_mov_b32 m0, s24
	s_nop 0
	global_load_lds_dwordx4 v[78:79], off
	s_mov_b32 m0, s27
	v_lshl_add_u64 v[78:79], v[208:209], 0, s[16:17]
	s_add_i32 s2, s2, s73
	s_mov_b32 s24, m0
	s_mov_b32 m0, s2
	s_nop 0
	global_load_lds_dwordx4 v[78:79], off
	s_mov_b32 m0, s24
	s_waitcnt lgkmcnt(14)
	v_mfma_f32_32x32x16_bf16 v[16:31], v[160:163], v[66:69], v[16:31]
	ds_read_b64_tr_b16 v[90:91], v214 offset:32768
	ds_read_b64_tr_b16 v[92:93], v214 offset:33280
	v_exp_f32_e32 v128, v128
	v_exp_f32_e32 v129, v129
	s_waitcnt lgkmcnt(14)
	v_mfma_f32_32x32x16_bf16 v[48:63], v[160:163], v[70:73], v[48:63]
	ds_read_b64_tr_b16 v[188:189], v214 offset:36864
	ds_read_b64_tr_b16 v[190:191], v214 offset:37376
	v_exp_f32_e32 v130, v130
	v_exp_f32_e32 v131, v131
	v_add_u32_e32 v66, s25, v246
	ds_read_b128 v[82:85], v66
	ds_read_b128 v[78:81], v66 offset:512
	s_waitcnt lgkmcnt(14)
	v_mfma_f32_32x32x16_bf16 v[16:31], v[152:155], v[74:77], v[16:31]
	ds_read_b64_tr_b16 v[192:193], v214 offset:33792
	ds_read_b64_tr_b16 v[194:195], v214 offset:34304
	v_exp_f32_e32 v132, v132
	v_exp_f32_e32 v133, v133
	ds_read_b128 v[184:187], v66 offset:2048
	ds_read_b128 v[176:179], v66 offset:2560
	v_mfma_f32_32x32x16_bf16 v[48:63], v[152:155], v[96:99], v[48:63]
	ds_read_b64_tr_b16 v[196:197], v214 offset:37888
	ds_read_b64_tr_b16 v[198:199], v214 offset:38400
	v_exp_f32_e32 v134, v134
	v_exp_f32_e32 v135, v135
	ds_read_b128 v[180:183], v66 offset:4096
	ds_read_b128 v[70:73], v66 offset:4608
	s_waitcnt lgkmcnt(14)
	v_mfma_f32_32x32x16_bf16 v[16:31], v[148:151], v[100:103], v[16:31]
	ds_read_b64_tr_b16 v[94:95], v214 offset:34816
	ds_read_b64_tr_b16 v[96:97], v214 offset:35328
	v_exp_f32_e32 v136, v136
	v_exp_f32_e32 v137, v137
	ds_read_b128 v[74:77], v66 offset:6144
	ds_read_b128 v[66:69], v66 offset:6656
	v_mfma_f32_32x32x16_bf16 v[48:63], v[148:151], v[104:107], v[48:63]
	ds_read_b64_tr_b16 v[98:99], v214 offset:38912
	ds_read_b64_tr_b16 v[100:101], v214 offset:39424
	v_exp_f32_e32 v138, v138
	v_exp_f32_e32 v139, v139
	v_mfma_f32_32x32x16_bf16 v[16:31], v[144:147], v[108:111], v[16:31]
	ds_read_b64_tr_b16 v[102:103], v214 offset:35840
	ds_read_b64_tr_b16 v[104:105], v214 offset:36352
	v_exp_f32_e32 v140, v140
	v_exp_f32_e32 v141, v141
	v_mfma_f32_32x32x16_bf16 v[48:63], v[144:147], v[86:89], v[48:63]
	ds_read_b64_tr_b16 v[106:107], v214 offset:39936
	ds_read_b64_tr_b16 v[108:109], v214 offset:40448
	v_exp_f32_e32 v142, v142
	v_exp_f32_e32 v143, v143
	s_waitcnt lgkmcnt(14)
	v_mfma_f32_32x32x16_bf16 v[0:15], v[160:163], v[90:93], v[0:15]
	v_exp_f32_e32 v112, v112
	v_exp_f32_e32 v113, v113
	v_mfma_f32_32x32x16_bf16 v[32:47], v[160:163], v[188:191], v[32:47]
	v_exp_f32_e32 v114, v114
	v_exp_f32_e32 v115, v115
	v_mfma_f32_32x32x16_bf16 v[0:15], v[152:155], v[192:195], v[0:15]
	v_exp_f32_e32 v116, v116
	v_exp_f32_e32 v117, v117
	s_waitcnt lgkmcnt(12)
	v_mfma_f32_32x32x16_bf16 v[32:47], v[152:155], v[196:199], v[32:47]
	v_exp_f32_e32 v118, v118
	v_exp_f32_e32 v119, v119
	s_waitcnt lgkmcnt(8)
	v_mfma_f32_32x32x16_bf16 v[0:15], v[148:151], v[94:97], v[0:15]
	v_exp_f32_e32 v120, v120
	v_exp_f32_e32 v121, v121
	s_waitcnt lgkmcnt(4)
	v_mfma_f32_32x32x16_bf16 v[32:47], v[148:151], v[98:101], v[32:47]
	v_exp_f32_e32 v122, v122
	v_exp_f32_e32 v123, v123
	s_waitcnt lgkmcnt(2)
	v_mfma_f32_32x32x16_bf16 v[0:15], v[144:147], v[102:105], v[0:15]
	v_exp_f32_e32 v124, v124
	v_exp_f32_e32 v125, v125
	s_waitcnt lgkmcnt(0)
	v_mfma_f32_32x32x16_bf16 v[32:47], v[144:147], v[106:109], v[32:47]
	v_exp_f32_e32 v126, v126
	v_exp_f32_e32 v127, v127
	s_add_i32 s2, s25, 0x2000
	s_cmpk_lg_i32 s25, 0x4000
	s_cselect_b32 s2, s2, 0
	s_waitcnt vmcnt(3) lgkmcnt(0)
	s_barrier
	v_lshl_add_u32 v214, s1, 1, v248
	ds_read_b64_tr_b16 v[188:189], v214 offset:24576
	ds_read_b64_tr_b16 v[190:191], v214 offset:25088
	v_mfma_f32_32x32x16_bf16 v[96:111], v[82:85], v[172:175], 0
	v_add_f32_e32 v86, v128, v129
	v_add_f32_e32 v86, v130, v86
	v_add_f32_e32 v86, v131, v86
	v_add_f32_e32 v86, v132, v86
	v_add_f32_e32 v86, v133, v86
	v_cvt_pk_bf16_f32 v160, v128, v129
	v_cvt_pk_bf16_f32 v161, v130, v131
	ds_read_b64_tr_b16 v[128:129], v214 offset:28672
	ds_read_b64_tr_b16 v[130:131], v214 offset:29184
	v_add_f32_e32 v82, v134, v86
	v_add_f32_e32 v82, v135, v82
	v_add_f32_e32 v82, v136, v82
	v_add_f32_e32 v144, v137, v82
	v_mfma_f32_32x32x16_bf16 v[80:95], v[78:81], v[172:175], 0
	v_cvt_pk_bf16_f32 v162, v132, v133
	v_cvt_pk_bf16_f32 v163, v134, v135
	ds_read_b64_tr_b16 v[132:133], v214 offset:25600
	ds_read_b64_tr_b16 v[134:135], v214 offset:26112
	v_mfma_f32_32x32x16_bf16 v[96:111], v[184:187], v[168:171], v[96:111]
	v_add_f32_e32 v78, v138, v144
	v_add_f32_e32 v78, v139, v78
	v_add_f32_e32 v78, v140, v78
	v_add_f32_e32 v78, v141, v78
	v_cvt_pk_bf16_f32 v152, v136, v137
	v_cvt_pk_bf16_f32 v153, v138, v139
	ds_read_b64_tr_b16 v[136:137], v214 offset:29696
	ds_read_b64_tr_b16 v[138:139], v214 offset:30208
	v_mfma_f32_32x32x16_bf16 v[80:95], v[176:179], v[168:171], v[80:95]
	v_add_f32_e32 v78, v142, v78
	v_add_f32_e32 v78, v143, v78
	v_add_f32_e32 v78, v112, v78
	v_add_f32_e32 v78, v113, v78
	v_cvt_pk_bf16_f32 v154, v140, v141
	v_cvt_pk_bf16_f32 v155, v142, v143
	ds_read_b64_tr_b16 v[140:141], v214 offset:26624
	ds_read_b64_tr_b16 v[142:143], v214 offset:27136
	v_mfma_f32_32x32x16_bf16 v[96:111], v[180:183], v[164:167], v[96:111]
	v_add_f32_e32 v78, v114, v78
	v_add_f32_e32 v78, v115, v78
	v_add_f32_e32 v78, v116, v78
	v_add_f32_e32 v78, v117, v78
	v_cvt_pk_bf16_f32 v148, v112, v113
	v_cvt_pk_bf16_f32 v149, v114, v115
	ds_read_b64_tr_b16 v[112:113], v214 offset:30720
	ds_read_b64_tr_b16 v[114:115], v214 offset:31232
	v_mfma_f32_32x32x16_bf16 v[80:95], v[70:73], v[164:167], v[80:95]
	v_add_f32_e32 v78, v118, v78
	v_add_f32_e32 v78, v119, v78
	v_add_f32_e32 v78, v120, v78
	v_add_f32_e32 v78, v121, v78
	v_cvt_pk_bf16_f32 v150, v116, v117
	v_cvt_pk_bf16_f32 v151, v118, v119
	ds_read_b64_tr_b16 v[70:71], v214 offset:27648
	ds_read_b64_tr_b16 v[72:73], v214 offset:28160
	v_mfma_f32_32x32x16_bf16 v[96:111], v[74:77], v[156:159], v[96:111]
	v_add_f32_e32 v78, v122, v78
	v_add_f32_e32 v78, v123, v78
	v_add_f32_e32 v78, v124, v78
	v_add_f32_e32 v78, v125, v78
	v_cvt_pk_bf16_f32 v144, v120, v121
	v_cvt_pk_bf16_f32 v145, v122, v123
	ds_read_b64_tr_b16 v[74:75], v214 offset:31744
	ds_read_b64_tr_b16 v[76:77], v214 offset:32256
	v_mfma_f32_32x32x16_bf16 v[80:95], v[66:69], v[156:159], v[80:95]
	v_add_f32_e32 v78, v126, v78
	v_add_f32_e32 v78, v127, v78
	v_add_f32_e32 v78, 0, v78
	v_cvt_pk_bf16_f32 v146, v124, v125
	v_cvt_pk_bf16_f32 v147, v126, v127
	s_add_i32 s1, s25, s69
	s_mov_b32 s24, m0
	s_mov_b32 m0, s1
	s_nop 0
	global_load_lds_dwordx4 v[212:213], off
	s_mov_b32 m0, s24
	s_lshl_b32 s1, s2, 1
	s_add_i32 s24, s1, s72
	s_mov_b32 s27, m0
	s_mov_b32 m0, s24
	s_nop 0
	global_load_lds_dwordx4 v[210:211], off
	s_mov_b32 m0, s27
	s_add_i32 s1, s1, s73
	s_mov_b32 s24, m0
	s_mov_b32 m0, s1
	s_nop 0
	global_load_lds_dwordx4 v[208:209], off
	s_mov_b32 m0, s24
	s_add_i32 s8, s8, 2
	s_waitcnt lgkmcnt(14)
	v_mfma_f32_32x32x16_bf16 v[16:31], v[160:163], v[188:191], v[16:31]
	ds_read_b64_tr_b16 v[66:67], v214 offset:32768
	ds_read_b64_tr_b16 v[68:69], v214 offset:33280
	v_exp_f32_e32 v96, v96
	v_exp_f32_e32 v97, v97
	s_waitcnt lgkmcnt(14)
	v_mfma_f32_32x32x16_bf16 v[48:63], v[160:163], v[128:131], v[48:63]
	ds_read_b64_tr_b16 v[116:117], v214 offset:36864
	ds_read_b64_tr_b16 v[118:119], v214 offset:37376
	v_exp_f32_e32 v98, v98
	v_exp_f32_e32 v99, v99
	v_add_u32_e32 v79, s2, v246
	ds_read_b128 v[204:207], v79
	ds_read_b128 v[200:203], v79 offset:512
	s_waitcnt lgkmcnt(14)
	v_mfma_f32_32x32x16_bf16 v[16:31], v[152:155], v[132:135], v[16:31]
	ds_read_b64_tr_b16 v[120:121], v214 offset:33792
	ds_read_b64_tr_b16 v[122:123], v214 offset:34304
	v_exp_f32_e32 v100, v100
	v_exp_f32_e32 v101, v101
	ds_read_b128 v[196:199], v79 offset:2048
	ds_read_b128 v[192:195], v79 offset:2560
	v_mfma_f32_32x32x16_bf16 v[48:63], v[152:155], v[136:139], v[48:63]
	ds_read_b64_tr_b16 v[124:125], v214 offset:37888
	ds_read_b64_tr_b16 v[126:127], v214 offset:38400
	v_exp_f32_e32 v102, v102
	v_exp_f32_e32 v103, v103
	ds_read_b128 v[188:191], v79 offset:4096
	ds_read_b128 v[184:187], v79 offset:4608
	s_waitcnt lgkmcnt(14)
	v_mfma_f32_32x32x16_bf16 v[16:31], v[148:151], v[140:143], v[16:31]
	ds_read_b64_tr_b16 v[128:129], v214 offset:34816
	ds_read_b64_tr_b16 v[130:131], v214 offset:35328
	v_exp_f32_e32 v104, v104
	v_exp_f32_e32 v105, v105
	ds_read_b128 v[180:183], v79 offset:6144
	ds_read_b128 v[176:179], v79 offset:6656
	v_mfma_f32_32x32x16_bf16 v[48:63], v[148:151], v[112:115], v[48:63]
	ds_read_b64_tr_b16 v[132:133], v214 offset:38912
	ds_read_b64_tr_b16 v[134:135], v214 offset:39424
	v_exp_f32_e32 v106, v106
	v_exp_f32_e32 v107, v107
	v_mfma_f32_32x32x16_bf16 v[16:31], v[144:147], v[70:73], v[16:31]
	ds_read_b64_tr_b16 v[112:113], v214 offset:35840
	ds_read_b64_tr_b16 v[114:115], v214 offset:36352
	v_exp_f32_e32 v108, v108
	v_exp_f32_e32 v109, v109
	v_mfma_f32_32x32x16_bf16 v[48:63], v[144:147], v[74:77], v[48:63]
	ds_read_b64_tr_b16 v[70:71], v214 offset:39936
	ds_read_b64_tr_b16 v[72:73], v214 offset:40448
	v_exp_f32_e32 v110, v110
	v_exp_f32_e32 v111, v111
	s_waitcnt lgkmcnt(14)
	v_mfma_f32_32x32x16_bf16 v[0:15], v[160:163], v[66:69], v[0:15]
	v_exp_f32_e32 v80, v80
	v_exp_f32_e32 v81, v81
	v_mfma_f32_32x32x16_bf16 v[32:47], v[160:163], v[116:119], v[32:47]
	v_exp_f32_e32 v82, v82
	v_exp_f32_e32 v83, v83
	v_mfma_f32_32x32x16_bf16 v[0:15], v[152:155], v[120:123], v[0:15]
	v_exp_f32_e32 v84, v84
	v_exp_f32_e32 v85, v85
	s_waitcnt lgkmcnt(12)
	v_mfma_f32_32x32x16_bf16 v[32:47], v[152:155], v[124:127], v[32:47]
	v_exp_f32_e32 v86, v86
	v_exp_f32_e32 v87, v87
	s_waitcnt lgkmcnt(8)
	v_mfma_f32_32x32x16_bf16 v[0:15], v[148:151], v[128:131], v[0:15]
	v_exp_f32_e32 v88, v88
	v_exp_f32_e32 v89, v89
	s_waitcnt lgkmcnt(4)
	v_mfma_f32_32x32x16_bf16 v[32:47], v[148:151], v[132:135], v[32:47]
	v_exp_f32_e32 v90, v90
	v_exp_f32_e32 v91, v91
	s_waitcnt lgkmcnt(2)
	v_mfma_f32_32x32x16_bf16 v[0:15], v[144:147], v[112:115], v[0:15]
	v_exp_f32_e32 v92, v92
	v_exp_f32_e32 v93, v93
	s_waitcnt lgkmcnt(0)
	v_mfma_f32_32x32x16_bf16 v[32:47], v[144:147], v[70:73], v[32:47]
	v_exp_f32_e32 v94, v94
	v_exp_f32_e32 v95, v95
	s_add_i32 s1, s2, 0x2000
	v_add_f32_e32 v64, v64, v65
	s_cmpk_lg_i32 s2, 0x4000
	v_lshl_add_u64 v[208:209], v[208:209], 0, s[12:13]
	v_lshl_add_u64 v[210:211], v[210:211], 0, s[12:13]
	v_lshl_add_u64 v[212:213], v[212:213], 0, s[12:13]
	s_mov_b32 s27, s25
	s_cselect_b32 s24, s1, 0
	s_cmp_ge_i32 s8, s0
	v_add_f32_e32 v64, v64, v78
	s_waitcnt vmcnt(3) lgkmcnt(0)
	s_barrier
	s_cbranch_scc0 .LBB0_647
	s_add_i32 s0, s8, 1
	s_cmp_ge_i32 s0, s26
	s_mov_b64 s[0:1], -1
	s_cbranch_scc0 .LBB0_650
